# rms and ctx LayerNorm rows spread over all workgroups (row index = wave*256 + workgroup) instead of the first 128 workgroups
# baseline (speedup 1.0000x reference)
; #define REPLOOP(k) _Pragma("unroll 1") for (int rep_ = 0, nrep_ = (phase_group(k) == DUP_GROUP ? 2 : 1); rep_ < nrep_; ++rep_)
; #define INP(k) input_ptr(args, (k))
; __global__ void __launch_bounds__(NTHR, 2) fwd(Args args) {
;     ...
;             const int pid = Lb + (which == 0 ? 8 : 11);
;             if (layer < DEPTH - 1 && IN(pid)) { REPLOOP(pid) { PH_BEGIN(); LAYER_VARS();
;                 const float* lg = INP(I_LNG) + (size_t)(layer * 2 + which) * D; const float* lb = INP(I_LNB) + (size_t)(layer * 2 + which) * D;
;                 const float* mp = (which == 0 ? modl + 3 * D : modl + 5 * MODW) + 4 * MODW;
;                 const float* gp = modl + 4 * MODW + (which == 0 ? 2 : 5) * D + lane * 4;
;                 for (int row = RL + gw; row < R; row += NGW) {
;                     const float* hp0 = (layer == 0 && which == 0 ? INP(I_CTX) + (size_t)(row - RL) * D : Hs + (size_t)row * D) + lane * 4; const float* pk = (const float*)(ws + X_PARTK) + (size_t)(row - RL) * D + lane * 4;
;                     f32x4 v[8]; float s = 0.f;
; #pragma unroll
;                     for (int j = 0; j < 8; ++j) { f32x4 a = *(const f32x4*)(pk + 256 * j);
; #pragma unroll
;                         for (int ks = 1; ks < 8; ++ks) a += *(const f32x4*)(pk + (size_t)ks * RC * D + 256 * j);
;                         v[j] = *(const f32x4*)(hp0 + 256 * j) * ALPHA + *(const f32x4*)(gp + 256 * j) * a; s += (v[j][0] + v[j][1]) + (v[j][2] + v[j][3]); }
.LBB0_766:
	s_waitcnt lgkmcnt(0)
	s_add_i32 s4, s88, 8
	s_cmp_le_i32 s90, s4
	s_cselect_b64 s[2:3], -1, 0
	s_cmp_lt_i32 s4, s91
	s_cselect_b64 s[4:5], -1, 0
	s_and_b64 s[2:3], s[2:3], s[4:5]
	s_andn2_b64 vcc, exec, s[2:3]
	s_cbranch_vccnz .LBB0_824
	s_load_dword s20, s[86:87], 0x0
	v_mov_b32_e32 v0, 27
	s_waitcnt vmcnt(0)
	v_mov_b32_e32 v3, s96
	v_readfirstlane_b32 s2, v0
	v_mbcnt_lo_u32_b32 v0, -1, 0
	v_mbcnt_hi_u32_b32 v0, -1, v0
	s_waitcnt lgkmcnt(0)
	v_mov_b32_e32 v4, s20
	v_or_b32_e32 v2, s85, v0
	s_nop 0
	v_readfirstlane_b32 s3, v3
	v_readfirstlane_b32 s4, v2
	s_ashr_i32 s5, s4, 6
	s_lshl_b32 s5, s5, 8
	s_mov_b32 s6, s3
	s_add_i32 s10, s5, s6
	s_cmpk_gt_i32 s10, 0x23ff
	v_readfirstlane_b32 s4, v4
	s_cbranch_scc1 .LBB0_770
	s_ashr_i32 s3, s2, 31
	s_lshl_b64 s[2:3], s[2:3], 3
	s_add_u32 s2, s0, s2
	s_addc_u32 s3, s1, s3
	s_load_dwordx2 s[2:3], s[2:3], 0x0
	s_lshl_b32 s4, s4, 3
	s_ashr_i32 s7, s5, 31
	s_ashr_i32 s11, s6, 31
	s_add_u32 s6, s5, s6
	s_addc_u32 s7, s7, s11
	s_lshl_b64 s[6:7], s[6:7], 13
	v_and_b32_e32 v0, 63, v0
	s_waitcnt lgkmcnt(0)
	s_add_u32 s2, s2, s6
	v_lshlrev_b32_e32 v2, 2, v0
	v_lshlrev_b32_e32 v0, 4, v0
	s_addc_u32 s3, s3, s7
	v_xor_b32_e32 v12, 4, v2
	v_xor_b32_e32 v13, 8, v2
	v_xor_b32_e32 v14, 16, v2
	v_xor_b32_e32 v15, 32, v2
	v_xor_b32_e32 v16, 64, v2
	v_xor_b32_e32 v17, 0x80, v2
	v_lshl_add_u64 v[2:3], s[2:3], 0, v[0:1]
	s_mov_b64 s[2:3], 0x24f00000
	s_ashr_i32 s5, s4, 31
	v_lshl_add_u64 v[6:7], v[2:3], 0, s[2:3]
	s_lshl_b64 s[6:7], s[4:5], 13

; #define REPLOOP(k) _Pragma("unroll 1") for (int rep_ = 0, nrep_ = (phase_group(k) == DUP_GROUP ? 2 : 1); rep_ < nrep_; ++rep_)
; #define INP(k) input_ptr(args, (k))
; __global__ void __launch_bounds__(NTHR, 2) fwd(Args args) {
;     ...
;             if (layer < DEPTH - 1 && IN(pid)) { REPLOOP(pid) { PH_BEGIN(); LAYER_VARS();
;                 const float* lg = INP(I_LNG) + (size_t)(layer * 2 + which) * D; const float* lb = INP(I_LNB) + (size_t)(layer * 2 + which) * D;
;                 const float* mp = (which == 0 ? modl + 3 * D : modl + 5 * MODW) + 4 * MODW;
;                 const float* gp = modl + 4 * MODW + (which == 0 ? 2 : 5) * D + lane * 4;
;                 for (int row = RL + gw; row < R; row += NGW) {
;                     const float* hp0 = (layer == 0 && which == 0 ? INP(I_CTX) + (size_t)(row - RL) * D : Hs + (size_t)row * D) + lane * 4; const float* pk = (const float*)(ws + X_PARTK) + (size_t)(row - RL) * D + lane * 4;
;                     f32x4 v[8]; float s = 0.f;
; #pragma unroll
;                     for (int j = 0; j < 8; ++j) { f32x4 a = *(const f32x4*)(pk + 256 * j);
; #pragma unroll
;                         for (int ks = 1; ks < 8; ++ks) a += *(const f32x4*)(pk + (size_t)ks * RC * D + 256 * j);
;                         v[j] = *(const f32x4*)(hp0 + 256 * j) * ALPHA + *(const f32x4*)(gp + 256 * j) * a; s += (v[j][0] + v[j][1]) + (v[j][2] + v[j][3]); }
;                     f32x4 lgv[8], lbv[8], shv[8], scv[8];
; #pragma unroll
;                     for (int j = 0; j < 8; ++j) { const int c = lane * 4 + 256 * j; lgv[j] = *(const f32x4*)(lg + c); lbv[j] = *(const f32x4*)(lb + c); shv[j] = *(const f32x4*)(mp + c); scv[j] = *(const f32x4*)(mp + D + c); }
.LBB0_2023:
	s_and_b64 s[2:3], s[80:81], exec
	s_cselect_b32 s22, 8, 11
	s_add_i32 s22, s22, s94
	s_cmp_le_i32 s90, s22
	s_cselect_b64 s[2:3], -1, 0
	s_and_b64 s[2:3], s[12:13], s[2:3]
	s_cmp_lt_i32 s22, s91
	s_waitcnt lgkmcnt(0)
	s_cselect_b64 s[4:5], -1, 0
	s_and_b64 s[2:3], s[2:3], s[4:5]
	s_andn2_b64 vcc, exec, s[2:3]
	s_cbranch_vccnz .LBB0_1751
	s_load_dword s14, s[86:87], 0x0
	v_mov_b32_e32 v0, 27
	s_waitcnt vmcnt(0)
	v_mov_b32_e32 v3, s96
	v_readfirstlane_b32 s2, v0
	v_mbcnt_lo_u32_b32 v0, -1, 0
	v_mbcnt_hi_u32_b32 v0, -1, v0
	s_waitcnt lgkmcnt(0)
	v_mov_b32_e32 v4, s14
	v_or_b32_e32 v2, s85, v0
	s_nop 0
	v_readfirstlane_b32 s3, v3
	v_readfirstlane_b32 s5, v2
	s_ashr_i32 s5, s5, 6
	s_lshl_b32 s5, s5, 8
	v_mov_b32_e32 v2, 6
	s_add_i32 s30, s3, s5
	v_readfirstlane_b32 s8, v2
	v_mov_b32_e32 v2, 7
	s_add_i32 s36, s30, 0x2000
	v_readfirstlane_b32 s4, v4
	s_cmpk_gt_i32 s36, 0x23ff
	v_readfirstlane_b32 s6, v2
	s_cbranch_scc1 .LBB0_2031
	s_ashr_i32 s3, s2, 31
	s_lshl_b64 s[2:3], s[2:3], 3
	s_add_u32 s2, s0, s2
	s_addc_u32 s3, s1, s3
	s_load_dwordx2 s[2:3], s[2:3], 0x0
	s_lshl_b32 s38, s4, 3
	v_lshlrev_b32_e32 v3, 2, v0
	v_and_b32_e32 v2, 0xfc, v3
	v_lshlrev_b32_e32 v0, 2, v2
	s_waitcnt lgkmcnt(0)
	s_add_u32 s4, s2, 0x19b00000
	s_addc_u32 s5, s3, 0
	s_add_u32 s7, s2, s78
	s_addc_u32 s9, s3, s79
	s_add_u32 s7, s7, 0x100000
	s_addc_u32 s23, s9, 0
	s_ashr_i32 s9, s8, 31
	s_lshl_b64 s[8:9], s[8:9], 3
	s_add_u32 s8, s0, s8
	s_addc_u32 s9, s1, s9
	s_and_b64 s[16:17], s[80:81], exec
	s_cselect_b32 s16, 0x4000, s95
	s_add_u32 s16, s7, s16
	s_addc_u32 s17, s23, 0
	v_lshl_add_u64 v[4:5], s[16:17], 0, v[0:1]
	s_mov_b64 s[16:17], 0x30000
	v_lshl_add_u64 v[114:115], v[4:5], 0, s[16:17]
	s_and_b64 s[16:17], s[80:81], exec
	s_mov_b32 s16, 0x3c000
	s_cselect_b32 s16, 0x6000, s16
	s_add_u32 s28, s7, s16
	s_addc_u32 s23, s23, 0
	s_add_u32 s16, s28, 0x30000
	s_addc_u32 s17, s23, 0
	s_ashr_i32 s7, s6, 31
	s_lshl_b64 s[6:7], s[6:7], 3
	s_add_u32 s6, s0, s6
	s_addc_u32 s7, s1, s7
	s_load_dwordx2 s[8:9], s[8:9], 0x0
	s_nop 0
	s_load_dwordx2 s[6:7], s[6:7], 0x0
	s_lshl_b32 s24, s33, 11
	v_readlane_b32 s26, v255, 46
	v_readlane_b32 s27, v255, 47
	s_or_b32 s24, s24, s26
	s_lshl_b64 s[26:27], s[24:25], 2
	s_waitcnt lgkmcnt(0)
	s_add_u32 s6, s6, s26
	s_addc_u32 s7, s7, s27
	s_add_u32 s8, s8, s26
	s_addc_u32 s9, s9, s27
	v_readlane_b32 s26, v255, 44
	v_readlane_b32 s27, v255, 45
	s_or_b32 s24, s33, s26
	s_cmp_lg_u32 s24, 0
	v_lshl_add_u64 v[6:7], s[2:3], 0, v[0:1]
	s_mov_b64 s[26:27], 0x2ef00000
	s_cselect_b64 s[40:41], -1, 0
	v_lshl_add_u64 v[118:119], v[6:7], 0, s[26:27]
	s_add_u32 s26, s28, 0x32000
	s_mov_b64 s[28:29], 0x31000
	v_lshl_add_u64 v[120:121], v[4:5], 0, s[28:29]
	s_mov_b64 s[28:29], 0x31400
	v_lshl_add_u64 v[122:123], v[4:5], 0, s[28:29]
	s_mov_b64 s[28:29], 0x31800
	v_lshl_add_u64 v[124:125], v[4:5], 0, s[28:29]
	s_mov_b64 s[28:29], 0x31c00
	s_addc_u32 s27, s23, 0
	v_lshl_add_u64 v[126:127], v[4:5], 0, s[28:29]
	v_or_b32_e32 v4, 0x400, v0
	v_mov_b32_e32 v5, v1
	v_lshl_add_u64 v[136:137], s[16:17], 0, v[4:5]
	v_lshl_add_u64 v[138:139], s[26:27], 0, v[4:5]
	v_or_b32_e32 v4, 0x800, v0
	v_lshl_add_u64 v[140:141], s[16:17], 0, v[4:5]
	v_lshl_add_u64 v[142:143], s[26:27], 0, v[4:5]
	v_or_b32_e32 v4, 0xc00, v0
	v_lshl_add_u64 v[144:145], s[16:17], 0, v[4:5]
	v_lshl_add_u64 v[146:147], s[26:27], 0, v[4:5]
	v_or_b32_e32 v4, 0x1000, v0
	v_lshl_add_u64 v[148:149], s[8:9], 0, v[4:5]
	v_lshl_add_u64 v[150:151], s[6:7], 0, v[4:5]
	v_lshl_add_u64 v[152:153], s[16:17], 0, v[4:5]
	v_lshl_add_u64 v[154:155], s[26:27], 0, v[4:5]
	v_or_b32_e32 v4, 0x1400, v0
	v_lshl_add_u64 v[116:117], s[4:5], 0, v[0:1]
	v_lshl_add_u64 v[128:129], s[8:9], 0, v[0:1]
	v_lshl_add_u64 v[130:131], s[6:7], 0, v[0:1]
	v_lshl_add_u64 v[132:133], s[16:17], 0, v[0:1]
	v_lshl_add_u64 v[134:135], s[26:27], 0, v[0:1]
	v_lshl_add_u64 v[156:157], s[8:9], 0, v[4:5]
	v_lshl_add_u64 v[158:159], s[6:7], 0, v[4:5]
	v_lshl_add_u64 v[160:161], s[16:17], 0, v[4:5]
	v_lshl_add_u64 v[162:163], s[26:27], 0, v[4:5]
	v_or_b32_e32 v4, 0x1800, v0
	v_or_b32_e32 v0, 0x1c00, v0
	v_lshl_add_u64 v[172:173], s[8:9], 0, v[0:1]
	v_lshl_add_u64 v[174:175], s[6:7], 0, v[0:1]
	v_lshl_add_u64 v[176:177], s[16:17], 0, v[0:1]
	v_lshl_add_u64 v[178:179], s[26:27], 0, v[0:1]
	v_lshlrev_b32_e32 v0, 1, v2
	v_lshl_add_u64 v[164:165], s[8:9], 0, v[4:5]
	v_lshl_add_u64 v[166:167], s[6:7], 0, v[4:5]
	v_lshl_add_u64 v[168:169], s[16:17], 0, v[4:5]
	v_lshl_add_u64 v[170:171], s[26:27], 0, v[4:5]
	v_lshl_add_u64 v[4:5], s[2:3], 0, v[0:1]
	s_mov_b64 s[2:3], 0x22b00000
	s_ashr_i32 s37, s36, 31
	v_lshl_add_u64 v[180:181], v[4:5], 0, s[2:3]
	s_ashr_i32 s39, s38, 31
	s_lshl_b64 s[2:3], s[36:37], 13
	v_bfrev_b32_e32 v6, 0.5
	s_movk_i32 s23, 0x80
	s_add_u32 s42, s4, s2
	v_bitop3_b32 v218, v3, 4, v6 bitop3:0x6c
	v_bitop3_b32 v219, v3, 8, v6 bitop3:0x6c
	v_bitop3_b32 v220, v3, 16, v6 bitop3:0x6c
	v_bitop3_b32 v221, v3, 32, v6 bitop3:0x6c
	v_bitop3_b32 v222, v3, 64, v6 bitop3:0x6c
	v_bitop3_b32 v223, v3, s23, v6 bitop3:0x6c
	s_addc_u32 s43, s5, s3
	s_lshl_b64 s[50:51], s[38:39], 13
	v_lshlrev_b32_e32 v0, 2, v2
	s_branch .LBB0_2028
